# P4: four interleave groups (role*2+bit3): DFT GEMM tiles run after 0..3 of the block's scan items
# baseline (speedup 1.0000x reference)
.LBB0_449:
	s_or_b64 exec, exec, s[0:1]
	v_writelane_b32 v253, s76, 42
	s_cmpk_gt_i32 s55, 0x23f
	s_waitcnt lgkmcnt(0)
	v_writelane_b32 v253, s77, 43
	v_writelane_b32 v253, s78, 44
	v_writelane_b32 v253, s79, 45
	v_writelane_b32 v253, s80, 46
	v_writelane_b32 v253, s81, 47
	v_writelane_b32 v253, s82, 48
	v_writelane_b32 v253, s83, 49
	s_barrier
	s_cbranch_scc1 .LBB0_494
	v_readlane_b32 s98, v255, 45
	s_bfe_u32 s99, s55, 0x10003
	s_nop 0
	s_lshl_b32 s98, s98, 1
	s_or_b32 s98, s98, s99
	v_writelane_b32 v255, s98, 44
	s_mov_b32 s99, 0
	v_writelane_b32 v255, s99, 43
	s_lshl_b32 s99, s98, 9
	s_cmp_eq_u32 s98, 0
	s_cselect_b32 s99, 0x600, s99
	s_cselect_b32 s98, 0, 1
	v_writelane_b32 v255, s98, 47
	s_cbranch_scc0 .LBB0_494

.LBB0_494:
	s_sub_i32 s70, s55, 64
	s_cmp_lt_i32 s70, 0
	s_cselect_b32 s0, s92, 0
	s_add_i32 s70, s70, s0
	v_readlane_b32 s98, v255, 43
	s_nop 1
	s_add_i32 s70, s70, s98
	s_mov_b64 s[0:1], s[36:37]
	s_mov_b64 s[12:13], s[48:49]
	s_mov_b64 s[2:3], s[38:39]
	s_mov_b64 s[4:5], s[40:41]
	s_mov_b64 s[6:7], s[42:43]
	s_mov_b64 s[14:15], s[50:51]
	s_mov_b64 s[10:11], s[46:47]
	v_writelane_b32 v253, s0, 50
	s_cmpk_gt_i32 s70, 0x5ff
	s_nop 0
	v_writelane_b32 v253, s1, 51
	v_writelane_b32 v253, s2, 52
	v_writelane_b32 v253, s3, 53
	v_writelane_b32 v253, s4, 54
	v_writelane_b32 v253, s5, 55
	v_writelane_b32 v253, s6, 56
	v_writelane_b32 v253, s7, 57
	v_writelane_b32 v253, s8, 58
	v_writelane_b32 v253, s9, 59
	v_writelane_b32 v253, s10, 60
	v_writelane_b32 v253, s11, 61
	v_writelane_b32 v253, s12, 62
	v_writelane_b32 v255, s14, 0
	v_writelane_b32 v253, s13, 63
	v_writelane_b32 v255, s15, 1
	s_cbranch_scc1 .LBB0_697
	s_add_u32 s0, s42, 0xfffff400
	s_addc_u32 s1, s43, -1
	v_writelane_b32 v255, s0, 2
	v_readlane_b32 s76, v253, 26
	s_movk_i32 s52, 0xa000
	v_writelane_b32 v255, s1, 3
	s_add_u32 s0, s40, 0xfffff400
	s_addc_u32 s1, s41, -1
	v_writelane_b32 v255, s0, 4
	v_mov_b32_e32 v65, 0
	s_movk_i32 s71, 0x1c00
	v_writelane_b32 v255, s1, 5
	v_readlane_b32 s0, v254, 34
	v_readlane_b32 s1, v254, 35
	v_readlane_b32 s4, v254, 38
	v_readlane_b32 s5, v254, 39
	v_mov_b32_e32 v85, s1
	v_mov_b32_e32 v86, s4
	v_mov_b32_e32 v84, s5
	v_mov_b32_e32 v87, s0
	s_movk_i32 s53, 0x90
	v_mov_b32_e32 v88, 0x3ecc95a3
	v_mov_b32_e32 v89, 0x1800
	v_mov_b32_e32 v90, 0x7f800000
	v_mov_b32_e32 v91, 0x1e00
	v_mov_b32_e32 v92, 0x1c00
	v_mov_b32_e32 v93, 0x200
	v_mov_b32_e32 v94, 0x1a00
	v_mov_b32_e32 v95, 0x400
	v_mov_b32_e32 v96, 0x600
	v_mov_b32_e32 v97, 0x1600
	v_mov_b32_e32 v98, 0x800
	v_mov_b32_e32 v99, 0x1400
	v_mov_b32_e32 v100, 0xa00
	v_mov_b32_e32 v101, 0x1200
	v_mov_b32_e32 v102, 0xc00
	v_mov_b32_e32 v103, 0x1000
	v_mov_b32_e32 v104, 0xe00
	v_readlane_b32 s77, v253, 27
	v_readlane_b32 s78, v253, 28
	v_readlane_b32 s79, v253, 29
	v_readlane_b32 s80, v253, 30
	v_readlane_b32 s81, v253, 31
	v_readlane_b32 s82, v253, 32
	v_readlane_b32 s83, v253, 33
	v_readlane_b32 s84, v253, 34
	v_readlane_b32 s85, v253, 35
	v_readlane_b32 s86, v253, 36
	v_readlane_b32 s87, v253, 37
	v_readlane_b32 s88, v253, 38
	v_readlane_b32 s89, v253, 39
	v_readlane_b32 s90, v253, 40
	v_readlane_b32 s91, v253, 41
	v_readlane_b32 s2, v254, 36
	v_readlane_b32 s3, v254, 37
	v_readlane_b32 s6, v254, 40
	v_readlane_b32 s7, v254, 41
	v_readlane_b32 s8, v254, 42
	v_readlane_b32 s9, v254, 43
	v_readlane_b32 s10, v254, 44
	v_readlane_b32 s11, v254, 45
	v_readlane_b32 s12, v254, 46
	v_readlane_b32 s13, v254, 47
	v_readlane_b32 s14, v254, 48
	v_readlane_b32 s15, v254, 49
	s_branch .LBB0_497
.LBB0_496:
	s_or_b64 exec, exec, s[0:1]
	s_add_i32 s70, s70, s92
	s_cmp_lt_i32 s70, s99
	s_barrier
	s_cbranch_scc0 .LBB0_696

.LBB0_696:
	v_readlane_b32 s98, v255, 47
	s_nop 1
	s_cmp_eq_u32 s98, 1
	s_cbranch_scc0 .Lp4_noswap
	s_mov_b32 s98, 2
	v_writelane_b32 v255, s98, 47
	v_readlane_b32 s98, v253, 4
	v_readlane_b32 s99, v253, 5
	s_nop 1
	s_sub_u32 s98, s98, 0x228
	s_subb_u32 s99, s99, 0
	s_load_dwordx16 s[36:51], s[98:99], 0x158
	s_waitcnt lgkmcnt(0)
	s_branch .Lp4_gemm_pre
.Lp4_gemm_exit:
	v_readlane_b32 s98, v255, 47
	s_nop 1
	s_movk_i32 s99, 0x600
	s_cmp_eq_u32 s98, 2
	s_cbranch_scc0 .LBB0_494
	v_readlane_b32 s98, v255, 44
	s_nop 1
	s_cmp_eq_u32 s98, 3
	s_cbranch_scc1 .Lp4_noswap
	s_lshl_b32 s98, s98, 9
	v_writelane_b32 v255, s98, 43
	s_mov_b32 s98, 3
	s_nop 0
	v_writelane_b32 v255, s98, 47
	s_branch .LBB0_494
